# v016 + SWA prologue wait removed + FoX Q loads issued together (vmcnt(4)) + P6 consumer partial loads in one batch
# speedup vs baseline: 1.0127x; 1.0009x over previous
; #define LAS __attribute__((address_space(3)))
; __device__ __forceinline__ float bflo(unsigned w) { return __uint_as_float(w << 16); }
; __device__ __forceinline__ float bfhi(unsigned w) { return __uint_as_float(w & 0xffff0000u); }
; __device__ __forceinline__ float xsum(float v) { const auto r = __builtin_amdgcn_permlane32_swap(__float_as_uint(v), __float_as_uint(v), false, false); return __uint_as_float(r[0]) + __uint_as_float(r[1]); }
;     ...
;     float qn = 0.f; bool wdone = false;
;     LAS unsigned* flg = (LAS unsigned*)(lds + 2 * AT_BUF);
;     if (MODE == 0) {
; #pragma unroll
;         for (int ks = 0; ks < 8; ++ks) { const u32x4 qq = __builtin_bit_cast(u32x4, qf[ks]);
;             qn += bflo(qq.x) * bflo(qq.x) + bfhi(qq.x) * bfhi(qq.x) + bflo(qq.y) * bflo(qq.y) + bfhi(qq.y) * bfhi(qq.y) + bflo(qq.z) * bflo(qq.z) + bfhi(qq.z) * bfhi(qq.z) + bflo(qq.w) * bflo(qq.w) + bfhi(qq.w) * bfhi(qq.w); }
;         qn = xsum(qn); qn = sqrtf(qn) * kn * SC * 1.0001f + 1e-3f;
; __global__ void __launch_bounds__(512, 2) hybrid_fwd(Params p) {
;     ...
;                     const int qb = 31 - (u >> 2), hd = u & 3, tq0 = 256 * qb + 32 * wave, t_row = tq0 + (lane & 31);
;                     attn_unit<0>(lds, tid, PROJ + (size_t)t_row * NP + PJ_FQ + hd * 128, PROJ + PJ_FK + hd * 128, NP, VT + (size_t)(VT_F + hd * 128) * T_, T_,
;                                  0, 4 * (qb + 1), t_row, tq0, CC + (size_t)hd * T_, NEG, 0.f, nullptr, O + (size_t)t_row * D_ + hd * 128, sqrtf(__uint_as_float(KNB[l * 4 + hd])));
.LBB0_568:
	s_lshl_b32 s0, s2, 6
	s_and_b32 s12, s0, 0xffffff00
	s_lshl_b32 s0, s3, 5
	s_sub_i32 s13, s0, s12
	s_add_i32 s3, s13, 0x1f00
	s_and_b32 s14, s2, 3
	v_and_or_b32 v146, v144, 31, s3
	v_mov_b64_e32 v[0:1], s[8:9]
	v_mad_i64_i32 v[0:1], s[0:1], v146, s56, v[0:1]
	s_lshl_b32 s72, s14, 8
	s_add_u32 s0, s8, s72
	s_addc_u32 s1, s9, 0
	s_add_u32 s6, s0, 0x1f600400
	s_addc_u32 s7, s1, 0
	s_lshl_b32 s0, s14, 21
	s_add_u32 s0, s8, s0
	s_addc_u32 s1, s9, 0
	s_and_b32 s4, s2, -4
	s_lshl_b32 s5, s14, 15
	s_add_u32 s5, s8, s5
	s_addc_u32 s11, s9, 0
	s_add_u32 s10, s5, 0x38f00000
	v_lshl_add_u64 v[0:1], v[0:1], 0, s[72:73]
	s_addc_u32 s11, s11, 0
	s_or_b32 s72, s14, s20
	s_lshl_b64 s[16:17], s[72:73], 2
	s_add_u32 s5, s8, s16
	s_addc_u32 s15, s9, s17
	v_mov_b32_e32 v2, s5
	s_mov_b32 s5, 0x38f80000
	v_add_co_u32_e32 v2, vcc, s5, v2
	v_mov_b32_e32 v3, s15
	s_nop 0
	v_addc_co_u32_e32 v3, vcc, 0, v3, vcc
	v_mov_b32_e32 v145, v144
	flat_load_dword v6, v[2:3]
	s_mov_b64 s[16:17], 0x1f600000
	v_bfe_u32 v7, v145, 5, 1
	v_lshlrev_b32_e32 v200, 4, v7
	v_lshl_add_u64 v[0:1], v[0:1], 0, v[200:201]
	s_mov_b32 s5, 0x1f600000
	v_lshl_add_u64 v[2:3], v[0:1], 0, s[16:17]
	v_add_co_u32_e32 v0, vcc, s5, v0
	s_sub_i32 s15, 0x7f, s4
	s_nop 0
	v_addc_co_u32_e32 v1, vcc, 0, v1, vcc
	flat_load_dwordx4 v[96:99], v[0:1]
	flat_load_dwordx4 v[100:103], v[2:3] offset:32
	flat_load_dwordx4 v[104:107], v[2:3] offset:64
	flat_load_dwordx4 v[108:111], v[2:3] offset:96
	flat_load_dwordx4 v[112:115], v[2:3] offset:128
	flat_load_dwordx4 v[116:119], v[2:3] offset:160
	flat_load_dwordx4 v[120:123], v[2:3] offset:192
	flat_load_dwordx4 v[124:127], v[2:3] offset:224
	s_waitcnt vmcnt(4)
	v_ashrrev_i32_e32 v168, 4, v145
	s_lshl_b32 s72, s15, 6
	v_and_b32_e32 v10, 15, v145
	v_ashrrev_i32_e32 v0, 3, v145
	v_lshlrev_b32_e32 v148, 4, v10
	v_mov_b32_e32 v149, v201
	v_and_b32_e32 v11, 7, v145
	v_lshlrev_b32_e32 v150, 4, v11
	v_mov_b32_e32 v151, v201
	s_waitcnt lgkmcnt(0)
	v_and_b32_e32 v2, 0xffff0000, v96
	v_lshlrev_b32_e32 v1, 16, v96
	v_mul_f32_e32 v2, v2, v2
	v_fmac_f32_e32 v2, v1, v1
	v_lshlrev_b32_e32 v1, 16, v97
	v_fmac_f32_e32 v2, v1, v1
	v_and_b32_e32 v1, 0xffff0000, v97
	v_fmac_f32_e32 v2, v1, v1
	v_lshlrev_b32_e32 v1, 16, v98
	v_fmac_f32_e32 v2, v1, v1
	v_and_b32_e32 v1, 0xffff0000, v98
	v_fmac_f32_e32 v2, v1, v1
	v_lshlrev_b32_e32 v1, 16, v99
	v_fmac_f32_e32 v2, v1, v1
	v_and_b32_e32 v1, 0xffff0000, v99
	v_and_b32_e32 v3, 0xffff0000, v100
	v_fmac_f32_e32 v2, v1, v1
	v_lshlrev_b32_e32 v1, 16, v100
	v_mul_f32_e32 v3, v3, v3
	v_fmac_f32_e32 v3, v1, v1
	v_lshlrev_b32_e32 v1, 16, v101
	v_fmac_f32_e32 v3, v1, v1
	v_and_b32_e32 v1, 0xffff0000, v101
	v_fmac_f32_e32 v3, v1, v1
	v_lshlrev_b32_e32 v1, 16, v102
	v_fmac_f32_e32 v3, v1, v1
	v_and_b32_e32 v1, 0xffff0000, v102
	v_fmac_f32_e32 v3, v1, v1
	v_lshlrev_b32_e32 v1, 16, v103
	v_fmac_f32_e32 v3, v1, v1
	v_and_b32_e32 v1, 0xffff0000, v103
	v_fmac_f32_e32 v3, v1, v1
	v_add_f32_e32 v1, v2, v3
	v_and_b32_e32 v3, 0xffff0000, v104
	v_lshlrev_b32_e32 v2, 16, v104
	v_mul_f32_e32 v3, v3, v3
	v_fmac_f32_e32 v3, v2, v2
	v_lshlrev_b32_e32 v2, 16, v105
	v_fmac_f32_e32 v3, v2, v2
	v_and_b32_e32 v2, 0xffff0000, v105
	v_fmac_f32_e32 v3, v2, v2
	v_lshlrev_b32_e32 v2, 16, v106
	v_fmac_f32_e32 v3, v2, v2
	v_and_b32_e32 v2, 0xffff0000, v106
	v_fmac_f32_e32 v3, v2, v2
	v_lshlrev_b32_e32 v2, 16, v107
	v_fmac_f32_e32 v3, v2, v2
	v_and_b32_e32 v2, 0xffff0000, v107
	v_fmac_f32_e32 v3, v2, v2
	v_add_f32_e32 v1, v1, v3
	v_and_b32_e32 v3, 0xffff0000, v108
	v_lshlrev_b32_e32 v2, 16, v108
	v_mul_f32_e32 v3, v3, v3
	v_fmac_f32_e32 v3, v2, v2
	v_lshlrev_b32_e32 v2, 16, v109
	v_fmac_f32_e32 v3, v2, v2
	v_and_b32_e32 v2, 0xffff0000, v109
	v_fmac_f32_e32 v3, v2, v2
	v_lshlrev_b32_e32 v2, 16, v110
	v_fmac_f32_e32 v3, v2, v2
	v_and_b32_e32 v2, 0xffff0000, v110
	v_fmac_f32_e32 v3, v2, v2
	v_lshlrev_b32_e32 v2, 16, v111
	v_fmac_f32_e32 v3, v2, v2
	v_and_b32_e32 v2, 0xffff0000, v111
	v_fmac_f32_e32 v3, v2, v2
	v_add_f32_e32 v1, v1, v3
	s_waitcnt vmcnt(0)
; #define LAS __attribute__((address_space(3)))
; __device__ __forceinline__ float bflo(unsigned w) { return __uint_as_float(w << 16); }
; __device__ __forceinline__ float bfhi(unsigned w) { return __uint_as_float(w & 0xffff0000u); }
; __device__ __forceinline__ float xsum(float v) { const auto r = __builtin_amdgcn_permlane32_swap(__float_as_uint(v), __float_as_uint(v), false, false); return __uint_as_float(r[0]) + __uint_as_float(r[1]); }
;     ...
;     float qn = 0.f; bool wdone = false;
;     LAS unsigned* flg = (LAS unsigned*)(lds + 2 * AT_BUF);
;     if (MODE == 0) {
; #pragma unroll
;         for (int ks = 0; ks < 8; ++ks) { const u32x4 qq = __builtin_bit_cast(u32x4, qf[ks]);
;             qn += bflo(qq.x) * bflo(qq.x) + bfhi(qq.x) * bfhi(qq.x) + bflo(qq.y) * bflo(qq.y) + bfhi(qq.y) * bfhi(qq.y) + bflo(qq.z) * bflo(qq.z) + bfhi(qq.z) * bfhi(qq.z) + bflo(qq.w) * bflo(qq.w) + bfhi(qq.w) * bfhi(qq.w); }
;         qn = xsum(qn); qn = sqrtf(qn) * kn * SC * 1.0001f + 1e-3f;
;     }
	v_and_b32_e32 v3, 0xffff0000, v112
	v_lshlrev_b32_e32 v2, 16, v112
	v_mul_f32_e32 v3, v3, v3
	v_fmac_f32_e32 v3, v2, v2
	v_lshlrev_b32_e32 v2, 16, v113
	v_fmac_f32_e32 v3, v2, v2
	v_and_b32_e32 v2, 0xffff0000, v113
	v_fmac_f32_e32 v3, v2, v2
	v_lshlrev_b32_e32 v2, 16, v114
	v_fmac_f32_e32 v3, v2, v2
	v_and_b32_e32 v2, 0xffff0000, v114
	v_fmac_f32_e32 v3, v2, v2
	v_lshlrev_b32_e32 v2, 16, v115
	v_fmac_f32_e32 v3, v2, v2
	v_and_b32_e32 v2, 0xffff0000, v115
	v_fmac_f32_e32 v3, v2, v2
	v_add_f32_e32 v1, v1, v3
	v_and_b32_e32 v3, 0xffff0000, v116
	v_lshlrev_b32_e32 v2, 16, v116
	v_mul_f32_e32 v3, v3, v3
	v_fmac_f32_e32 v3, v2, v2
	v_lshlrev_b32_e32 v2, 16, v117
	v_fmac_f32_e32 v3, v2, v2
	v_and_b32_e32 v2, 0xffff0000, v117
	v_fmac_f32_e32 v3, v2, v2
	v_lshlrev_b32_e32 v2, 16, v118
	v_fmac_f32_e32 v3, v2, v2
	v_and_b32_e32 v2, 0xffff0000, v118
	v_fmac_f32_e32 v3, v2, v2
	v_lshlrev_b32_e32 v2, 16, v119
	v_fmac_f32_e32 v3, v2, v2
	v_and_b32_e32 v2, 0xffff0000, v119
	v_fmac_f32_e32 v3, v2, v2
	v_add_f32_e32 v1, v1, v3
	v_and_b32_e32 v3, 0xffff0000, v120
	v_lshlrev_b32_e32 v2, 16, v120
	v_mul_f32_e32 v3, v3, v3
	v_fmac_f32_e32 v3, v2, v2
	v_lshlrev_b32_e32 v2, 16, v121
	v_fmac_f32_e32 v3, v2, v2
	v_and_b32_e32 v2, 0xffff0000, v121
	v_fmac_f32_e32 v3, v2, v2
	v_lshlrev_b32_e32 v2, 16, v122
	v_fmac_f32_e32 v3, v2, v2
	v_and_b32_e32 v2, 0xffff0000, v122
	v_fmac_f32_e32 v3, v2, v2
	v_lshlrev_b32_e32 v2, 16, v123
	v_fmac_f32_e32 v3, v2, v2
	v_and_b32_e32 v2, 0xffff0000, v123
	v_fmac_f32_e32 v3, v2, v2
	v_add_f32_e32 v1, v1, v3
	v_and_b32_e32 v3, 0xffff0000, v124
	v_lshlrev_b32_e32 v2, 16, v124
	v_mul_f32_e32 v3, v3, v3
	v_fmac_f32_e32 v3, v2, v2
	v_lshlrev_b32_e32 v2, 16, v125
	v_fmac_f32_e32 v3, v2, v2
	v_and_b32_e32 v2, 0xffff0000, v125
	v_fmac_f32_e32 v3, v2, v2
	v_lshlrev_b32_e32 v2, 16, v126
	v_fmac_f32_e32 v3, v2, v2
	v_and_b32_e32 v2, 0xffff0000, v126
	v_fmac_f32_e32 v3, v2, v2
	v_lshlrev_b32_e32 v2, 16, v127
	v_fmac_f32_e32 v3, v2, v2
	v_and_b32_e32 v2, 0xffff0000, v127
	v_fmac_f32_e32 v3, v2, v2
	v_add_f32_e32 v8, v1, v3
	v_add_u32_e32 v1, s72, v168
	v_mov_b64_e32 v[2:3], s[6:7]
	v_mad_i64_i32 v[4:5], s[4:5], v1, s56, v[2:3]
	v_add_u32_e32 v1, 32, v1
	v_mad_i64_i32 v[2:3], s[4:5], v1, s56, v[2:3]
	v_lshl_add_u64 v[4:5], v[4:5], 0, v[148:149]
	v_lshl_add_u64 v[2:3], v[2:3], 0, v[148:149]
	v_ashrrev_i32_e32 v1, 31, v0
	flat_load_dwordx4 v[128:131], v[4:5]
	flat_load_dwordx4 v[132:135], v[2:3]
	v_lshlrev_b64 v[2:3], 14, v[0:1]
	v_lshl_add_u64 v[4:5], s[0:1], 0, v[2:3]
	s_mov_b64 s[0:1], 0x22f00000
	v_lshl_add_u64 v[2:3], v[4:5], 0, s[0:1]
	s_lshl_b64 s[0:1], s[72:73], 1
	v_lshl_add_u64 v[12:13], v[2:3], 0, s[0:1]
	s_mov_b64 s[4:5], 0x23000000
	v_lshl_add_u64 v[12:13], v[12:13], 0, v[150:151]
	v_lshl_add_u64 v[4:5], v[4:5], 0, s[4:5]
	flat_load_dwordx4 v[136:139], v[12:13]
	v_lshl_add_u64 v[12:13], v[4:5], 0, s[0:1]
	v_lshl_add_u64 v[12:13], v[12:13], 0, v[150:151]
	flat_load_dwordx4 v[140:143], v[12:13]
	v_mov_b32_e32 v9, v8
	s_nop 1
	v_permlane32_swap_b32_e32 v8, v9
	v_cmp_gt_i32_e64 s[0:1], 64, v145
	v_mov_b32_e32 v149, 0
	s_and_saveexec_b64 s[4:5], s[0:1]
	s_cbranch_execz .LBB0_570
	v_add_u32_e32 v12, s72, v145
	v_ashrrev_i32_e32 v13, 31, v12
	v_lshl_add_u64 v[12:13], v[12:13], 2, s[10:11]
	flat_load_dword v149, v[12:13]

; #define PG8_BAR __builtin_amdgcn_s_barrier()
;     __device__ __forceinline__ CU2 full(int i) const { const int Lx = i * G + c; CU2 u; tile_order(Lx, 33, 44, u.pm, u.pn); return u; }
; #define REPS(k) for (int rep_ = 0; rep_ < (((RPM) >> (k)) & 1) + 1; ++rep_)
; template <class Epi, class Sched, bool APERM = false, bool HALFN = false>
; __device__ __forceinline__ void gemm_phase(LAS unsigned char* lds, const int tid_in, const int K, const Sched& S, const Epi& E) {
;     ...
;         if (wr == 0) PG8_BAR;
;         { const Unit fu = S.full(ui); E(acc, fu, wr, wc, fr, fq); }
; __global__ void __launch_bounds__(512, 2) hybrid_fwd(Params p) {
;     ...
;         if (PH(6)) REPS(6) { PHB
;             SchedQH S{ws, l, G, c};
;             EpiB E;
;             pg8::gemm_phase<EpiB, SchedQH, false, true>(lds, tid, D_, S, E);
.Lp6_wait_done:
	s_or_b64 exec, exec, s[22:23]
	s_waitcnt vmcnt(0) lgkmcnt(0)
	s_barrier
	s_lshl_b32 s18, s24, 17
	s_lshl_b32 s19, s25, 8
	s_and_b32 s19, s19, 0x1c000
	s_add_i32 s18, s18, s19
	s_add_u32 s20, s50, 0x27600000
	s_addc_u32 s21, s51, 0
	s_add_u32 s20, s20, s18
	s_addc_u32 s21, s21, 0
	v_and_b32_e32 v96, 63, v147
	v_lshlrev_b32_e32 v96, 4, v96
	v_mov_b32_e32 v97, 0
	s_mov_b64 s[22:23], 0x1000
	v_lshl_add_u64 v[96:97], s[20:21], 0, v[96:97]
	global_load_dwordx4 v[102:105], v[96:97], off sc1
	global_load_dwordx4 v[106:109], v[96:97], off offset:1024 sc1
	global_load_dwordx4 v[110:113], v[96:97], off offset:2048 sc1
	global_load_dwordx4 v[114:117], v[96:97], off offset:3072 sc1
	v_lshl_add_u64 v[96:97], v[96:97], 0, s[22:23]
	global_load_dwordx4 v[118:121], v[96:97], off sc1
	global_load_dwordx4 v[122:125], v[96:97], off offset:1024 sc1
	global_load_dwordx4 v[126:129], v[96:97], off offset:2048 sc1
	global_load_dwordx4 v[130:133], v[96:97], off offset:3072 sc1
	v_lshl_add_u64 v[96:97], v[96:97], 0, s[22:23]
	global_load_dwordx4 v[148:151], v[96:97], off sc1
	global_load_dwordx4 v[152:155], v[96:97], off offset:1024 sc1
	global_load_dwordx4 v[156:159], v[96:97], off offset:2048 sc1
	global_load_dwordx4 v[160:163], v[96:97], off offset:3072 sc1
	v_lshl_add_u64 v[96:97], v[96:97], 0, s[22:23]
	global_load_dwordx4 v[164:167], v[96:97], off sc1
	global_load_dwordx4 v[168:171], v[96:97], off offset:1024 sc1
	global_load_dwordx4 v[172:175], v[96:97], off offset:2048 sc1
	global_load_dwordx4 v[176:179], v[96:97], off offset:3072 sc1
	s_waitcnt vmcnt(0)
	v_add_f32_e32 v0, v0, v102
	v_add_f32_e32 v1, v1, v103
	v_add_f32_e32 v2, v2, v104
	v_add_f32_e32 v3, v3, v105
	v_add_f32_e32 v4, v4, v106
	v_add_f32_e32 v5, v5, v107
	v_add_f32_e32 v6, v6, v108
	v_add_f32_e32 v7, v7, v109
	v_add_f32_e32 v8, v8, v110
	v_add_f32_e32 v9, v9, v111
	v_add_f32_e32 v10, v10, v112
	v_add_f32_e32 v11, v11, v113
	v_add_f32_e32 v12, v12, v114
	v_add_f32_e32 v13, v13, v115
	v_add_f32_e32 v14, v14, v116
	v_add_f32_e32 v15, v15, v117
	v_add_f32_e32 v16, v16, v118
	v_add_f32_e32 v17, v17, v119
	v_add_f32_e32 v18, v18, v120
	v_add_f32_e32 v19, v19, v121
	v_add_f32_e32 v20, v20, v122
	v_add_f32_e32 v21, v21, v123
	v_add_f32_e32 v22, v22, v124
	v_add_f32_e32 v23, v23, v125
	v_add_f32_e32 v24, v24, v126
	v_add_f32_e32 v25, v25, v127
	v_add_f32_e32 v26, v26, v128
	v_add_f32_e32 v27, v27, v129
	v_add_f32_e32 v28, v28, v130
	v_add_f32_e32 v29, v29, v131
	v_add_f32_e32 v30, v30, v132
	v_add_f32_e32 v31, v31, v133
	v_add_f32_e32 v32, v32, v148
	v_add_f32_e32 v33, v33, v149
	v_add_f32_e32 v34, v34, v150
	v_add_f32_e32 v35, v35, v151
	v_add_f32_e32 v36, v36, v152
	v_add_f32_e32 v37, v37, v153
	v_add_f32_e32 v38, v38, v154
	v_add_f32_e32 v39, v39, v155
	v_add_f32_e32 v40, v40, v156
	v_add_f32_e32 v41, v41, v157
	v_add_f32_e32 v42, v42, v158
	v_add_f32_e32 v43, v43, v159
	v_add_f32_e32 v44, v44, v160
	v_add_f32_e32 v45, v45, v161
	v_add_f32_e32 v46, v46, v162
	v_add_f32_e32 v47, v47, v163
	v_add_f32_e32 v48, v48, v164
	v_add_f32_e32 v49, v49, v165
	v_add_f32_e32 v50, v50, v166
	v_add_f32_e32 v51, v51, v167
	v_add_f32_e32 v52, v52, v168
	v_add_f32_e32 v53, v53, v169
	v_add_f32_e32 v54, v54, v170
	v_add_f32_e32 v55, v55, v171
	v_add_f32_e32 v56, v56, v172
	v_add_f32_e32 v57, v57, v173
	v_add_f32_e32 v58, v58, v174
	v_add_f32_e32 v59, v59, v175
	v_add_f32_e32 v60, v60, v176
	v_add_f32_e32 v61, v61, v177
	v_add_f32_e32 v62, v62, v178
	v_add_f32_e32 v63, v63, v179
